# static s_setprio 1 for waves 4-7 during the x3 phase (Toeplitz/W2 MFMA sections), reset at phase exit
# speedup vs baseline: 1.0059x; 1.0055x over previous
.LBB0_143:
	s_and_b64 vcc, exec, s[0:1]
	s_cbranch_vccz .LBB0_687
	v_readlane_b32 s0, v255, 3
	s_cmp_gt_i32 s0, 2
	s_mov_b64 s[0:1], -1
	s_cbranch_scc0 .LBB0_307
	v_readlane_b32 s0, v255, 3
	s_cmp_lt_i32 s0, 4
	s_mov_b64 s[0:1], -1
	s_cbranch_scc1 .LBB0_300
	v_readlane_b32 s0, v255, 3
	s_cmp_gt_i32 s0, 4
	s_mov_b64 s[0:1], -1
	s_cbranch_scc0 .LBB0_292
	s_mov_b32 s10, s61
	s_mov_b32 s42, s18
	v_mov_b32_e32 v0, v1
	s_cmpk_gt_i32 s10, 0xff
	s_mov_b64 s[34:35], 0x4000
	s_cbranch_scc1 .LBB0_291
	s_load_dwordx2 s[6:7], s[74:75], 0xf0
	v_mbcnt_lo_u32_b32 v0, -1, v0
	v_mbcnt_hi_u32_b32 v0, -1, v0
	v_add_u32_e32 v3, s67, v0
	v_and_b32_e32 v154, 15, v0
	s_waitcnt lgkmcnt(0)
	s_add_u32 s0, s6, 0x16c00000
	s_addc_u32 s1, s7, 0
	s_add_u32 s2, s6, 0x27c00000
	s_addc_u32 s3, s7, 0
	v_lshrrev_b32_e32 v0, 4, v3
	s_add_u32 s4, s6, 0x2c000000
	v_bfe_u32 v6, v3, 4, 2
	s_addc_u32 s5, s7, 0
	v_bfe_u32 v7, v0, 1, 1
	s_lshl_b32 s8, s42, 11
	v_lshlrev_b32_e32 v0, 4, v154
	v_lshl_or_b32 v155, v6, 2, s8
	v_lshl_add_u64 v[4:5], s[6:7], 0, v[0:1]
	s_mov_b64 s[8:9], 0x2a000000
	v_add_u32_e32 v10, 16, v0
	v_lshlrev_b32_e32 v0, 3, v6
	v_lshl_add_u64 v[104:105], v[4:5], 0, s[8:9]
	v_lshl_add_u64 v[4:5], s[6:7], 0, v[0:1]
	s_mov_b64 s[6:7], 0x1ec00000
	v_lshl_add_u64 v[108:109], v[4:5], 0, s[6:7]
	v_add_u32_e32 v4, 0x200, v3
	v_lshl_add_u32 v5, v4, 4, 16
	v_add_u32_e32 v159, 0x200, v5
	v_add_u32_e32 v5, 0x400, v3
	v_lshl_add_u32 v11, v5, 4, 16
	v_ashrrev_i32_e32 v165, 4, v4
	v_lshlrev_b32_e32 v112, 3, v4
	v_add_u32_e32 v160, 0x200, v11
	v_add_u32_e32 v11, 0x600, v3
	s_mov_b32 s6, 0x8200
	v_mul_lo_u32 v4, v165, s70
	v_ashrrev_i32_e32 v167, 4, v5
	v_add3_u32 v166, v10, v4, s6
	v_mul_lo_u32 v4, v167, s70
	v_ashrrev_i32_e32 v169, 4, v11
	v_add3_u32 v168, v10, v4, s6
	v_mul_lo_u32 v4, v169, s70
	v_add3_u32 v170, v10, v4, s6
	v_add_u32_e32 v4, 0x800, v3
	v_ashrrev_i32_e32 v171, 4, v4
	v_mul_lo_u32 v4, v171, s70
	v_add3_u32 v172, v10, v4, s6
	v_add_u32_e32 v4, 0xa00, v3
	v_ashrrev_i32_e32 v173, 4, v4
	v_mul_lo_u32 v4, v173, s70
	v_ashrrev_i32_e32 v153, 6, v3
	v_lshrrev_b32_e32 v2, 1, v3
	v_cmp_gt_i32_e64 s[38:39], 32, v3
	v_lshl_add_u32 v156, v3, 4, 16
	v_lshlrev_b32_e32 v110, 3, v3
	v_ashrrev_i32_e32 v163, 4, v3
	v_add3_u32 v174, v10, v4, s6
	v_add_u32_e32 v4, 0xc00, v3
	v_add_u32_e32 v3, 0xe00, v3
	v_ashrrev_i32_e32 v177, 4, v3
	v_mul_lo_u32 v3, v177, s70
	v_add3_u32 v178, v10, v3, s6
	v_mov_b32_e32 v3, 0x8800
	v_mad_u32_u24 v180, v154, s70, v3
	v_mov_b32_e32 v3, 0x9900
	v_mad_u32_u24 v181, v154, s70, v3
	v_mov_b32_e32 v3, 0xaa00
	v_mad_u32_u24 v182, v154, s70, v3
	v_mov_b32_e32 v3, 0xbb00
	v_mad_u32_u24 v183, v154, s70, v3
	v_mov_b32_e32 v3, 0xcc00
	v_mad_u32_u24 v184, v154, s70, v3
	v_mov_b32_e32 v3, 0xdd00
	v_and_b32_e32 v2, 8, v2
	v_mad_u32_u24 v185, v154, s70, v3
	v_mov_b32_e32 v3, 0xee00
	v_lshlrev_b32_e32 v9, 1, v2
	v_lshl_add_u32 v12, v11, 4, 16
	v_ashrrev_i32_e32 v175, 4, v4
	v_mad_u32_u24 v186, v154, s70, v3
	v_mov_b32_e32 v3, 0xff00
	v_lshlrev_b32_e32 v8, 9, v7
	v_add_u32_e32 v161, 0x200, v12
	v_mul_lo_u32 v12, v163, s70
	v_mul_lo_u32 v4, v175, s70
	v_mad_u32_u24 v187, v154, s70, v3
	v_lshl_or_b32 v3, v154, 5, v9
	v_lshlrev_b32_e32 v114, 3, v5
	v_lshlrev_b32_e32 v116, 3, v11
	v_add3_u32 v164, v10, v12, s6
	v_add3_u32 v176, v10, v4, s6
	v_lshl_or_b32 v4, v7, 12, v2
	v_lshl_add_u32 v179, v6, 4, 16
	v_sub_u32_e32 v3, v3, v8
	v_readlane_b32 s6, v254, 54
	v_lshlrev_b32_e32 v157, 13, v7
	v_lshl_add_u64 v[106:107], s[0:1], 0, v[0:1]
	v_ashrrev_i32_e32 v111, 31, v110
	v_add_u32_e32 v158, 0x200, v156
	v_ashrrev_i32_e32 v113, 31, v112
	v_ashrrev_i32_e32 v115, 31, v114
	v_ashrrev_i32_e32 v117, 31, v116
	v_mul_u32_u24_e32 v162, 0x110, v154
	v_add_u32_e32 v188, 64, v179
	v_add_u32_e32 v189, 0x80, v179
	v_add_u32_e32 v190, 0xc0, v179
	v_add_u32_e32 v191, s6, v3
	v_lshlrev_b32_e32 v118, 1, v2
	v_lshlrev_b32_e32 v120, 1, v0
	v_lshlrev_b32_e32 v122, 1, v4
	s_cmp_lt_u32 s67, 0x100
	s_cbranch_scc1 .Lmy_x3_prio_skip
	s_setprio 1
.Lmy_x3_prio_skip:
	s_branch .LBB0_150
.LBB0_149:
	s_add_i32 s10, s10, s66
	s_cmpk_gt_i32 s10, 0xff
	s_cbranch_scc1 .LBB0_291

.LBB0_291:
	s_setprio 0
	s_mov_b64 s[0:1], 0
	s_mov_b32 s18, s42
